# v25: v20 + packed f32 VALU beside MFMAs in P13/P2 (14 v_pk_mul/fma_f32) replaced by scalar pairs
# speedup vs baseline: 1.0012x; 1.0012x over previous
; DI void attn0_phase(const unsigned char* QKV, bf16_t* OG, float* LSE, LAS unsigned char* lds, int tid, int bid, int G) {
;     ...
;         const A0Unit x = a0_decode(u);
;         const int h = x.h, d = x.d, nb = x.nb, grp = x.grp;
;         const size_t tok0 = (size_t)x.b * SEQ + x.r;
;         const int iq = 16 * w + n, lq = nb * 128 + iq;
;         const size_t qtok = tok0 + (size_t)lq * d;
;     ...
; #pragma unroll
;         for (int tt = 0; tt < 9; ++tt)
; #pragma unroll
;             for (int j = 0; j < 4; ++j) { const int kf = 16 * (w + tt) + 4 * g4 + j; const bool ok = (kf >= iq) && (kf <= iq + 128) && (nb > 0 || kf >= 128);
;                 const float xx = ok ? s[tt][j] : -__builtin_inff(); s[tt][j] = xx; mx = fmaxf(mx, xx); }
;         mx = fmaxf(mx, __shfl_xor(mx, 16)); mx = fmaxf(mx, __shfl_xor(mx, 32));
.LBB0_416:
	s_ashr_i32 s38, s89, 11
	s_lshl_b32 s14, s38, 1
	s_lshr_b32 s39, 64, s14
	s_bfe_u32 s0, s89, 0x60004
	s_sub_i32 s15, 6, s14
	s_add_i32 s39, s39, -1
	s_lshr_b32 s15, s0, s15
	s_and_b32 s39, s39, s0
	s_and_b32 s0, s37, 0x2000
	s_or_b32 s0, s15, s0
	v_lshl_add_u32 v10, s39, 7, v98
	s_and_b32 s89, s89, 15
	v_ashrrev_i32_e32 v11, 31, v10
	s_cmp_lg_u32 s39, 0
	v_readlane_b32 s40, v254, 31
	v_lshlrev_b64 v[10:11], s14, v[10:11]
	s_cselect_b64 s[14:15], -1, 0
	v_readlane_b32 s41, v254, 32
	s_or_b64 vcc, s[40:41], s[14:15]
	v_readlane_b32 s40, v254, 29
	v_readlane_b32 s41, v254, 30
	s_and_b64 vcc, s[40:41], vcc
	v_readlane_b32 s40, v254, 35
	v_readlane_b32 s41, v254, 36
	v_cndmask_b32_e32 v9, v125, v80, vcc
	s_or_b64 vcc, s[40:41], s[14:15]
	v_readlane_b32 s40, v254, 33
	v_readlane_b32 s41, v254, 34
	s_and_b64 vcc, s[40:41], vcc
	v_readlane_b32 s40, v254, 39
	v_readlane_b32 s41, v254, 40
	v_cndmask_b32_e32 v80, v125, v81, vcc
	s_or_b64 vcc, s[40:41], s[14:15]
	v_readlane_b32 s40, v254, 37
	v_readlane_b32 s41, v254, 38
	s_and_b64 vcc, s[40:41], vcc
	v_readlane_b32 s40, v254, 43
	v_readlane_b32 s41, v254, 44
	v_cndmask_b32_e32 v82, v125, v82, vcc
	s_or_b64 vcc, s[40:41], s[14:15]
	v_readlane_b32 s40, v254, 41
	v_readlane_b32 s41, v254, 42
	s_and_b64 vcc, s[40:41], vcc
	v_readlane_b32 s40, v254, 47
	v_readlane_b32 s41, v254, 48
	v_cndmask_b32_e32 v83, v125, v83, vcc
	s_or_b64 vcc, s[40:41], s[14:15]
	v_readlane_b32 s40, v254, 45
	v_readlane_b32 s41, v254, 46
	s_and_b64 vcc, s[40:41], vcc
	v_readlane_b32 s40, v254, 51
	v_readlane_b32 s41, v254, 52
	v_cndmask_b32_e32 v76, v125, v76, vcc
	s_or_b64 vcc, s[40:41], s[14:15]
	v_readlane_b32 s40, v254, 49
	v_readlane_b32 s41, v254, 50
	s_and_b64 vcc, s[40:41], vcc
	v_readlane_b32 s40, v254, 55
	v_readlane_b32 s41, v254, 56
	v_cndmask_b32_e32 v77, v125, v77, vcc
	s_or_b64 vcc, s[40:41], s[14:15]
	v_readlane_b32 s40, v254, 53
	v_readlane_b32 s41, v254, 54
	s_and_b64 vcc, s[40:41], vcc
	v_readlane_b32 s40, v254, 59
	v_readlane_b32 s41, v254, 60
	v_cndmask_b32_e32 v78, v125, v78, vcc
	s_or_b64 vcc, s[40:41], s[14:15]
	v_readlane_b32 s40, v254, 57
	v_readlane_b32 s41, v254, 58
	s_and_b64 vcc, s[40:41], vcc
	v_readlane_b32 s40, v254, 63
	v_readlane_b32 s41, v255, 0
	v_cndmask_b32_e32 v79, v125, v79, vcc
	s_or_b64 vcc, s[40:41], s[14:15]
	v_readlane_b32 s40, v254, 61
	v_readlane_b32 s41, v254, 62
	s_and_b64 vcc, s[40:41], vcc
	v_readlane_b32 s40, v255, 3
	v_readlane_b32 s41, v255, 4
	v_cndmask_b32_e32 v72, v125, v72, vcc
	s_or_b64 vcc, s[40:41], s[14:15]
	v_readlane_b32 s40, v255, 1
	v_readlane_b32 s41, v255, 2
	s_and_b64 vcc, s[40:41], vcc
	v_readlane_b32 s40, v255, 7
	v_readlane_b32 s41, v255, 8
	v_cndmask_b32_e32 v73, v125, v73, vcc
	s_or_b64 vcc, s[40:41], s[14:15]
	v_readlane_b32 s40, v255, 5
	v_readlane_b32 s41, v255, 6
	s_and_b64 vcc, s[40:41], vcc
	v_readlane_b32 s40, v255, 11
	v_readlane_b32 s41, v255, 12
	v_cndmask_b32_e32 v74, v125, v74, vcc
	s_or_b64 vcc, s[40:41], s[14:15]
	v_readlane_b32 s40, v255, 9
	v_readlane_b32 s41, v255, 10
	s_and_b64 vcc, s[40:41], vcc
	v_readlane_b32 s40, v255, 15
	v_readlane_b32 s41, v255, 16
	v_cndmask_b32_e32 v75, v125, v75, vcc
	s_or_b64 vcc, s[40:41], s[14:15]
	v_readlane_b32 s40, v255, 13
	v_readlane_b32 s41, v255, 14
	s_and_b64 vcc, s[40:41], vcc
	v_readlane_b32 s40, v255, 19
	v_readlane_b32 s41, v255, 20
	v_cndmask_b32_e32 v68, v125, v68, vcc
	s_or_b64 vcc, s[40:41], s[14:15]
	v_readlane_b32 s40, v255, 17
	v_readlane_b32 s41, v255, 18
	s_and_b64 vcc, s[40:41], vcc
	v_readlane_b32 s40, v255, 23
	v_readlane_b32 s41, v255, 24
	v_cndmask_b32_e32 v69, v125, v69, vcc
	s_or_b64 vcc, s[40:41], s[14:15]
	v_readlane_b32 s40, v255, 21
	v_readlane_b32 s41, v255, 22
	s_and_b64 vcc, s[40:41], vcc
	v_readlane_b32 s40, v255, 27
	v_readlane_b32 s41, v255, 28
	v_cndmask_b32_e32 v70, v125, v70, vcc
	s_or_b64 vcc, s[40:41], s[14:15]
	v_readlane_b32 s40, v255, 25
	v_readlane_b32 s41, v255, 26
	s_and_b64 vcc, s[40:41], vcc
	v_readlane_b32 s40, v255, 31
	v_readlane_b32 s41, v255, 32
	v_cndmask_b32_e32 v71, v125, v71, vcc
	s_or_b64 vcc, s[40:41], s[14:15]
	v_readlane_b32 s40, v255, 29
	v_readlane_b32 s41, v255, 30
	s_and_b64 vcc, s[40:41], vcc
	v_cndmask_b32_e32 v64, v125, v64, vcc
	s_or_b64 vcc, s[42:43], s[14:15]
	s_and_b64 vcc, s[4:5], vcc
	v_cndmask_b32_e32 v93, v125, v65, vcc
	s_or_b64 vcc, s[44:45], s[14:15]
	s_and_b64 vcc, s[16:17], vcc
	v_cndmask_b32_e32 v66, v125, v66, vcc
	s_or_b64 vcc, s[46:47], s[14:15]
	s_and_b64 vcc, s[2:3], vcc
	v_cndmask_b32_e32 v67, v125, v67, vcc
	s_or_b64 vcc, s[48:49], s[14:15]
	s_and_b64 vcc, s[18:19], vcc
	v_cndmask_b32_e32 v60, v125, v60, vcc
	s_or_b64 vcc, s[50:51], s[14:15]
	v_lshl_add_u64 v[10:11], v[10:11], 0, s[0:1]
	s_mov_b32 s0, 0xff800000
	s_and_b64 vcc, s[86:87], vcc
	v_max3_f32 v81, v9, s0, v80
	v_cndmask_b32_e32 v61, v125, v61, vcc
	s_or_b64 vcc, s[52:53], s[14:15]
	v_max3_f32 v81, v81, v82, v83
	s_and_b64 vcc, s[20:21], vcc
	v_max3_f32 v81, v81, v76, v77
	v_cndmask_b32_e32 v62, v125, v62, vcc
	s_or_b64 vcc, s[54:55], s[14:15]
	v_max3_f32 v81, v81, v78, v79
	s_and_b64 vcc, s[6:7], vcc
	v_max3_f32 v81, v81, v72, v73
	v_cndmask_b32_e32 v63, v125, v63, vcc
	s_or_b64 vcc, s[56:57], s[14:15]
	v_max3_f32 v81, v81, v74, v75
	s_and_b64 vcc, s[22:23], vcc
	v_max3_f32 v81, v81, v68, v69
	v_cndmask_b32_e32 v56, v125, v56, vcc
	s_or_b64 vcc, s[58:59], s[14:15]
	v_max3_f32 v81, v81, v70, v71
	s_and_b64 vcc, s[92:93], vcc
	v_max3_f32 v65, v81, v64, v93
	v_cndmask_b32_e32 v81, v125, v57, vcc
	s_or_b64 vcc, s[60:61], s[14:15]
	s_and_b64 vcc, s[24:25], vcc
	v_cndmask_b32_e32 v127, v125, v58, vcc
	s_or_b64 vcc, s[62:63], s[14:15]
; DI void attn0_phase(const unsigned char* QKV, bf16_t* OG, float* LSE, LAS unsigned char* lds, int tid, int bid, int G) {
;     ...
;                 const float xx = ok ? s[tt][j] : -__builtin_inff(); s[tt][j] = xx; mx = fmaxf(mx, xx); }
;         mx = fmaxf(mx, __shfl_xor(mx, 16)); mx = fmaxf(mx, __shfl_xor(mx, 32));
;         const float msc = mx * SM_C; float lsum = 0.f;
; #pragma unroll
;         for (int tt = 0; tt < 9; ++tt)
; #pragma unroll
;             for (int j = 0; j < 4; ++j) { const float p = __builtin_amdgcn_exp2f(s[tt][j] * SM_C - msc); s[tt][j] = p; lsum += p; }
	s_and_b64 vcc, s[8:9], vcc
	v_cndmask_b32_e32 v128, v125, v59, vcc
	s_or_b64 vcc, s[64:65], s[14:15]
	s_and_b64 vcc, s[26:27], vcc
	v_cndmask_b32_e32 v129, v125, v52, vcc
	s_or_b64 vcc, s[66:67], s[14:15]
	s_and_b64 vcc, s[90:91], vcc
	v_cndmask_b32_e32 v130, v125, v53, vcc
	s_or_b64 vcc, s[68:69], s[14:15]
	s_and_b64 vcc, s[28:29], vcc
	v_cndmask_b32_e32 v54, v125, v54, vcc
	s_or_b64 vcc, s[70:71], s[14:15]
	s_and_b64 vcc, s[10:11], vcc
	v_max3_f32 v65, v65, v66, v67
	v_cndmask_b32_e32 v55, v125, v55, vcc
	s_or_b64 vcc, s[72:73], s[14:15]
	v_max3_f32 v65, v65, v60, v61
	s_and_b64 vcc, s[30:31], vcc
	v_max3_f32 v65, v65, v62, v63
	v_cndmask_b32_e32 v131, v125, v84, vcc
	s_or_b64 vcc, s[74:75], s[14:15]
	v_max3_f32 v57, v65, v56, v81
	s_and_b64 vcc, s[96:97], vcc
	v_max3_f32 v57, v57, v127, v128
	v_cndmask_b32_e32 v132, v125, v85, vcc
	s_or_b64 vcc, s[76:77], s[14:15]
	v_max3_f32 v52, v57, v129, v130
	s_and_b64 vcc, s[34:35], vcc
	s_or_b64 s[14:15], s[78:79], s[14:15]
	v_and_b32_e32 v57, 64, v124
	v_cndmask_b32_e32 v86, v125, v86, vcc
	s_and_b64 vcc, s[12:13], s[14:15]
	v_xor_b32_e32 v53, 16, v124
	v_add_u32_e32 v57, 64, v57
	v_max3_f32 v52, v52, v54, v55
	v_cndmask_b32_e32 v84, v125, v87, vcc
	v_cmp_lt_i32_e32 vcc, v53, v57
	v_max3_f32 v52, v52, v131, v132
	v_max3_f32 v52, v52, v86, v84
	v_cndmask_b32_e32 v53, v124, v53, vcc
	v_lshlrev_b32_e32 v87, 2, v53
	ds_bpermute_b32 v53, v87, v52
	s_ashr_i32 s39, s38, 31
	v_readlane_b32 s0, v254, 21
	v_readlane_b32 s40, v254, 27
	v_readlane_b32 s41, v254, 28
	s_waitcnt lgkmcnt(0)
	v_max_f32_e32 v53, v53, v53
	v_max_f32_e32 v52, v52, v53
	v_xor_b32_e32 v53, 32, v124
	v_cmp_lt_i32_e32 vcc, v53, v57
	s_nop 1
	v_cndmask_b32_e32 v53, v124, v53, vcc
	v_lshlrev_b32_e32 v133, 2, v53
	ds_bpermute_b32 v53, v133, v52
	s_waitcnt lgkmcnt(0)
	v_max_f32_e32 v53, v53, v53
	v_max_f32_e32 v85, v52, v53
	v_mul_f32_e32 v52, s36, v84
	v_mul_f32_e32 v53, s36, v85
	s_nop 0
	v_fma_f32 v9, v9, s36, -v53
	v_exp_f32_e32 v134, v9
	v_fma_f32 v57, v80, s36, -v53
	v_exp_f32_e32 v80, v57
	v_fma_f32 v57, v82, s36, -v53
	v_exp_f32_e32 v82, v57
	v_fma_f32 v57, v83, s36, -v53
	v_exp_f32_e32 v83, v57
	v_fma_f32 v57, v76, s36, -v53
	v_add_f32_e32 v9, 0, v134
	v_exp_f32_e32 v76, v57
	v_fma_f32 v57, v77, s36, -v53
	v_add_f32_e32 v9, v80, v9
	v_exp_f32_e32 v77, v57
	v_fma_f32 v57, v78, s36, -v53
	v_add_f32_e32 v9, v82, v9
	v_exp_f32_e32 v78, v57
	v_fma_f32 v57, v79, s36, -v53
	v_add_f32_e32 v9, v83, v9
	v_exp_f32_e32 v79, v57
	v_fma_f32 v57, v72, s36, -v53
	v_add_f32_e32 v9, v76, v9
	v_exp_f32_e32 v148, v57
	v_fma_f32 v57, v73, s36, -v53
	v_add_f32_e32 v9, v77, v9
	v_exp_f32_e32 v149, v57
	v_fma_f32 v57, v74, s36, -v53
	v_add_f32_e32 v9, v78, v9
	v_exp_f32_e32 v150, v57
	v_fma_f32 v57, v75, s36, -v53
	v_add_f32_e32 v9, v79, v9
	v_exp_f32_e32 v151, v57
	v_fma_f32 v57, v68, s36, -v53
	v_add_f32_e32 v9, v148, v9
	v_exp_f32_e32 v152, v57
	v_fma_f32 v57, v69, s36, -v53
	v_add_f32_e32 v9, v149, v9
	v_exp_f32_e32 v153, v57
	v_fma_f32 v57, v70, s36, -v53
	v_add_f32_e32 v9, v150, v9
	v_exp_f32_e32 v154, v57
	v_fma_f32 v57, v71, s36, -v53
	v_add_f32_e32 v9, v151, v9
	v_exp_f32_e32 v155, v57
	v_fma_f32 v57, v64, s36, -v53
	v_add_f32_e32 v9, v152, v9
	v_exp_f32_e32 v65, v57
	v_fma_f32 v57, v93, s36, -v53
	v_add_f32_e32 v9, v153, v9
	v_exp_f32_e32 v93, v57
	v_fma_f32 v57, v66, s36, -v53
	v_add_f32_e32 v9, v154, v9
	v_exp_f32_e32 v156, v57
	v_fma_f32 v57, v67, s36, -v53
	v_add_f32_e32 v9, v155, v9
	v_exp_f32_e32 v157, v57
	v_fma_f32 v57, v60, s36, -v53
	v_add_f32_e32 v9, v65, v9
	v_exp_f32_e32 v158, v57
	v_fma_f32 v57, v61, s36, -v53
	v_add_f32_e32 v9, v93, v9
	v_exp_f32_e32 v159, v57
	v_fma_f32 v57, v62, s36, -v53
	v_add_f32_e32 v9, v156, v9
	v_exp_f32_e32 v160, v57
	v_fma_f32 v57, v63, s36, -v53
	v_add_f32_e32 v9, v157, v9
	v_exp_f32_e32 v161, v57
	v_fma_f32 v56, v56, s36, -v53
	v_add_f32_e32 v9, v158, v9
	v_exp_f32_e32 v57, v56
	v_fma_f32 v56, v81, s36, -v53
	v_add_f32_e32 v9, v159, v9
	v_exp_f32_e32 v58, v56
	v_fma_f32 v56, v127, s36, -v53
	v_add_f32_e32 v9, v160, v9
	v_exp_f32_e32 v59, v56
	v_fma_f32 v56, v128, s36, -v53
	v_add_f32_e32 v9, v161, v9
	v_exp_f32_e32 v60, v56
	v_fma_f32 v56, v129, s36, -v53
	v_add_f32_e32 v9, v57, v9
	v_exp_f32_e32 v61, v56
	v_fma_f32 v56, v130, s36, -v53
	v_add_f32_e32 v9, v58, v9
	v_exp_f32_e32 v62, v56
	v_fma_f32 v54, v54, s36, -v53
	v_add_f32_e32 v9, v59, v9
	v_exp_f32_e32 v63, v54
	v_fma_f32 v54, v55, s36, -v53
	v_add_f32_e32 v9, v60, v9
	v_exp_f32_e32 v64, v54
	v_fma_f32 v54, v131, s36, -v53
	v_add_f32_e32 v9, v61, v9
	v_exp_f32_e32 v54, v54
	v_fma_f32 v55, v132, s36, -v53
	v_add_f32_e32 v9, v62, v9
	v_exp_f32_e32 v55, v55
	v_fma_f32 v56, v86, s36, -v53
	v_add_f32_e32 v9, v63, v9
	v_exp_f32_e32 v56, v56
	v_sub_f32_e32 v52, v52, v53
	v_add_f32_e32 v9, v64, v9
	v_exp_f32_e32 v52, v52
	v_add_f32_e32 v9, v54, v9
	v_add_f32_e32 v9, v55, v9
	v_add_f32_e32 v9, v56, v9
	v_add_f32_e32 v9, v52, v9
	ds_bpermute_b32 v53, v87, v9
	v_cvt_pk_bf16_f32 v66, v134, v80
	v_cvt_pk_bf16_f32 v67, v82, v83
	v_add_u32_e32 v82, v101, v99
	v_add_u32_e32 v83, v100, v104
	s_waitcnt lgkmcnt(0)
; __device__ __forceinline__ unsigned cvt_pk_bf16(float lo, float hi) { unsigned r; asm volatile("v_cvt_pk_bf16_f32 %0, %1, %2" : "=v"(r) : "v"(lo), "v"(hi)); return r; }
; #define LAS __attribute__((address_space(3)))
; DI void attn0_phase(const unsigned char* QKV, bf16_t* OG, float* LSE, LAS unsigned char* lds, int tid, int bid, int G) {
;     ...
;         lsum += __shfl_xor(lsum, 16); lsum += __shfl_xor(lsum, 32);
;         f32x4 o[8];
; #pragma unroll
;         for (int dt = 0; dt < 8; ++dt) o[dt] = (f32x4){0.f, 0.f, 0.f, 0.f};
; #pragma unroll
;         for (int kk = 0; kk < 5; ++kk) {
;             const int t0 = 2 * kk, t1 = 2 * kk + 1;
;             u32x4 pw; pw.x = pg8::cvt_pk_bf16(s[t0][0], s[t0][1]); pw.y = pg8::cvt_pk_bf16(s[t0][2], s[t0][3]);
;             if (t1 < 9) { pw.z = pg8::cvt_pk_bf16(s[t1 < 9 ? t1 : 8][0], s[t1 < 9 ? t1 : 8][1]); pw.w = pg8::cvt_pk_bf16(s[t1 < 9 ? t1 : 8][2], s[t1 < 9 ? t1 : 8][3]); } else { pw.z = 0u; pw.w = 0u; }
;             const bf16x8 pf = __builtin_bit_cast(bf16x8, pw);
;             int T1 = w + t1; T1 = T1 > 15 ? 15 : T1;
;             const int row0 = 16 * (w + t0) * 256, row1 = 16 * T1 * 256;
; #pragma unroll
;             for (int dt = 0; dt < 8; ++dt) {
;                 const int choff = ((2 * dt + (p4 >> 1)) ^ (2 * q4)) * 16;
;                 const s16x4 lo = __builtin_amdgcn_ds_read_tr16_b64_v4i16((LAS s16x4*)(vt + tr_base + row0 + choff));
;                 const s16x4 hi = __builtin_amdgcn_ds_read_tr16_b64_v4i16((LAS s16x4*)(vt + tr_base + row1 + choff));
;                 const bf16x8 vf = __builtin_shufflevector(lo, hi, 0, 1, 2, 3, 4, 5, 6, 7);
;                 o[dt] = __builtin_amdgcn_mfma_f32_16x16x32_bf16(vf, pf, o[dt], 0, 0, 0); }
	v_add_f32_e32 v9, v9, v53
	v_cvt_pk_bf16_f32 v68, v76, v77
	v_cvt_pk_bf16_f32 v69, v78, v79
	v_add_u32_e32 v53, v100, v99
	ds_read_b64_tr_b16 v[72:73], v82
	ds_read_b64_tr_b16 v[128:129], v83
	v_add_u32_e32 v74, v100, v102
	v_add_u32_e32 v76, v101, v102
	v_add_u32_e32 v78, v100, v103
	v_add_u32_e32 v80, v101, v103
	v_add_u32_e32 v83, v101, v104
	ds_bpermute_b32 v84, v133, v9
	ds_read_b64_tr_b16 v[70:71], v53
	ds_read_b64_tr_b16 v[74:75], v74
	ds_read_b64_tr_b16 v[76:77], v76
	ds_read_b64_tr_b16 v[78:79], v78
	ds_read_b64_tr_b16 v[80:81], v80
	ds_read_b64_tr_b16 v[130:131], v83
	ds_read_b64_tr_b16 v[132:133], v53 offset:128
	ds_read_b64_tr_b16 v[134:135], v82 offset:128
	v_add_u32_e32 v53, v100, v105
	ds_read_b64_tr_b16 v[136:137], v53
	v_add_u32_e32 v53, v101, v105
	ds_read_b64_tr_b16 v[138:139], v53
	v_add_u32_e32 v53, v100, v106
	ds_read_b64_tr_b16 v[140:141], v53
	v_add_u32_e32 v53, v101, v106
	ds_read_b64_tr_b16 v[142:143], v53
	v_add_u32_e32 v53, v100, v107
	ds_read_b64_tr_b16 v[144:145], v53
	v_add_u32_e32 v53, v101, v107
	ds_read_b64_tr_b16 v[146:147], v53
	v_add_u32_e32 v53, v108, v99
	v_add_u32_e32 v82, v109, v99
	s_waitcnt lgkmcnt(13)
	v_mfma_f32_16x16x32_bf16 v[70:73], v[70:73], v[66:69], 0
	v_add_u32_e32 v83, v108, v102
	v_add_f32_e32 v9, v9, v84
	v_div_scale_f32 v84, s[14:15], v9, v9, 1.0
	s_waitcnt lgkmcnt(11)
	v_mfma_f32_16x16x32_bf16 v[74:77], v[74:77], v[66:69], 0
	v_rcp_f32_e32 v86, v84
	s_lshl_b64 s[14:15], s[38:39], 26
	s_add_u32 s14, s0, s14
	s_waitcnt lgkmcnt(9)
	v_mfma_f32_16x16x32_bf16 v[78:81], v[78:81], v[66:69], 0
	v_fma_f32 v87, -v84, v86, 1.0
	v_fmac_f32_e32 v86, v87, v86
	v_div_scale_f32 v87, vcc, 1.0, v9, 1.0
	s_waitcnt lgkmcnt(8)
	v_mfma_f32_16x16x32_bf16 v[128:131], v[128:131], v[66:69], 0
	v_readlane_b32 s0, v254, 22
	s_addc_u32 s15, s0, s15
	s_lshl_b32 s0, s89, 8
	s_waitcnt lgkmcnt(6)
	v_mfma_f32_16x16x32_bf16 v[132:135], v[132:135], v[66:69], 0
	s_waitcnt lgkmcnt(4)
	v_mfma_f32_16x16x32_bf16 v[136:139], v[136:139], v[66:69], 0
	s_waitcnt lgkmcnt(2)
	v_mfma_f32_16x16x32_bf16 v[140:143], v[140:143], v[66:69], 0
	s_waitcnt lgkmcnt(0)
	v_mfma_f32_16x16x32_bf16 v[66:69], v[144:147], v[66:69], 0
	v_cvt_pk_bf16_f32 v144, v148, v149
	v_cvt_pk_bf16_f32 v145, v150, v151
	v_cvt_pk_bf16_f32 v146, v152, v153
	v_cvt_pk_bf16_f32 v147, v154, v155
	ds_read_b64_tr_b16 v[148:149], v53
	ds_read_b64_tr_b16 v[150:151], v82
	s_waitcnt lgkmcnt(0)
	v_mfma_f32_16x16x32_bf16 v[70:73], v[148:151], v[144:147], v[70:73]
	ds_read_b64_tr_b16 v[148:149], v83
	v_add_u32_e32 v83, v109, v102
	ds_read_b64_tr_b16 v[150:151], v83
	v_add_u32_e32 v83, v108, v103
	s_waitcnt lgkmcnt(0)
	v_mfma_f32_16x16x32_bf16 v[74:77], v[148:151], v[144:147], v[74:77]
	ds_read_b64_tr_b16 v[148:149], v83
	v_add_u32_e32 v83, v109, v103
	ds_read_b64_tr_b16 v[150:151], v83
	v_add_u32_e32 v83, v108, v104
	s_waitcnt lgkmcnt(0)
	v_mfma_f32_16x16x32_bf16 v[78:81], v[148:151], v[144:147], v[78:81]
	ds_read_b64_tr_b16 v[148:149], v83
	v_add_u32_e32 v83, v109, v104
	ds_read_b64_tr_b16 v[150:151], v83
	s_waitcnt lgkmcnt(0)
	v_mfma_f32_16x16x32_bf16 v[128:131], v[148:151], v[144:147], v[128:131]
	ds_read_b64_tr_b16 v[148:149], v53 offset:128
	ds_read_b64_tr_b16 v[150:151], v82 offset:128
	v_add_u32_e32 v53, v108, v105
	v_add_u32_e32 v82, v110, v102
	s_waitcnt lgkmcnt(0)
	v_mfma_f32_16x16x32_bf16 v[132:135], v[148:151], v[144:147], v[132:135]
	ds_read_b64_tr_b16 v[148:149], v53
	v_add_u32_e32 v53, v109, v105
	ds_read_b64_tr_b16 v[150:151], v53
	v_add_u32_e32 v53, v108, v106
	s_waitcnt lgkmcnt(0)
	v_mfma_f32_16x16x32_bf16 v[136:139], v[148:151], v[144:147], v[136:139]
	ds_read_b64_tr_b16 v[148:149], v53
	v_add_u32_e32 v53, v109, v106
	ds_read_b64_tr_b16 v[150:151], v53
	v_add_u32_e32 v53, v108, v107
	s_waitcnt lgkmcnt(0)
	v_mfma_f32_16x16x32_bf16 v[140:143], v[148:151], v[144:147], v[140:143]
	ds_read_b64_tr_b16 v[148:149], v53
	v_add_u32_e32 v53, v109, v107
	ds_read_b64_tr_b16 v[150:151], v53
	s_waitcnt lgkmcnt(0)
	v_mfma_f32_16x16x32_bf16 v[66:69], v[148:151], v[144:147], v[66:69]
	v_cvt_pk_bf16_f32 v144, v65, v93
	v_add_u32_e32 v53, v110, v99
	v_add_u32_e32 v65, v111, v99
	v_cvt_pk_bf16_f32 v145, v156, v157
	v_cvt_pk_bf16_f32 v146, v158, v159
	v_cvt_pk_bf16_f32 v147, v160, v161
	ds_read_b64_tr_b16 v[148:149], v53
	ds_read_b64_tr_b16 v[150:151], v65
	s_waitcnt lgkmcnt(0)
	v_mfma_f32_16x16x32_bf16 v[70:73], v[148:151], v[144:147], v[70:73]
	ds_read_b64_tr_b16 v[148:149], v82
	v_add_u32_e32 v82, v111, v102
	ds_read_b64_tr_b16 v[150:151], v82
	v_add_u32_e32 v82, v110, v103
	s_waitcnt lgkmcnt(0)
	v_mfma_f32_16x16x32_bf16 v[74:77], v[148:151], v[144:147], v[74:77]
	ds_read_b64_tr_b16 v[148:149], v82
	v_add_u32_e32 v82, v111, v103
	ds_read_b64_tr_b16 v[150:151], v82
	v_add_u32_e32 v82, v110, v104
	s_waitcnt lgkmcnt(0)
	v_mfma_f32_16x16x32_bf16 v[78:81], v[148:151], v[144:147], v[78:81]
	ds_read_b64_tr_b16 v[148:149], v82
	v_add_u32_e32 v82, v111, v104
	ds_read_b64_tr_b16 v[150:151], v82
	s_waitcnt lgkmcnt(0)
	v_mfma_f32_16x16x32_bf16 v[128:131], v[148:151], v[144:147], v[128:131]
	ds_read_b64_tr_b16 v[148:149], v53 offset:128
	ds_read_b64_tr_b16 v[150:151], v65 offset:128
	v_add_u32_e32 v53, v110, v105
	v_mov_b32_e32 v154, v8
	s_waitcnt lgkmcnt(0)
	v_mfma_f32_16x16x32_bf16 v[132:135], v[148:151], v[144:147], v[132:135]
	ds_read_b64_tr_b16 v[148:149], v53
	v_add_u32_e32 v53, v111, v105
	ds_read_b64_tr_b16 v[150:151], v53
	v_add_u32_e32 v53, v110, v106
	s_waitcnt lgkmcnt(0)
	v_mfma_f32_16x16x32_bf16 v[136:139], v[148:151], v[144:147], v[136:139]
	ds_read_b64_tr_b16 v[148:149], v53
	v_add_u32_e32 v53, v111, v106
	ds_read_b64_tr_b16 v[150:151], v53
	v_add_u32_e32 v53, v110, v107
	s_waitcnt lgkmcnt(0)
; __device__ __forceinline__ unsigned cvt_pk_bf16(float lo, float hi) { unsigned r; asm volatile("v_cvt_pk_bf16_f32 %0, %1, %2" : "=v"(r) : "v"(lo), "v"(hi)); return r; }
; #define LAS __attribute__((address_space(3)))
; DI void attn0_phase(const unsigned char* QKV, bf16_t* OG, float* LSE, LAS unsigned char* lds, int tid, int bid, int G) {
;     ...
;         for (int kk = 0; kk < 5; ++kk) {
;             const int t0 = 2 * kk, t1 = 2 * kk + 1;
;             u32x4 pw; pw.x = pg8::cvt_pk_bf16(s[t0][0], s[t0][1]); pw.y = pg8::cvt_pk_bf16(s[t0][2], s[t0][3]);
;             if (t1 < 9) { pw.z = pg8::cvt_pk_bf16(s[t1 < 9 ? t1 : 8][0], s[t1 < 9 ? t1 : 8][1]); pw.w = pg8::cvt_pk_bf16(s[t1 < 9 ? t1 : 8][2], s[t1 < 9 ? t1 : 8][3]); } else { pw.z = 0u; pw.w = 0u; }
;             const bf16x8 pf = __builtin_bit_cast(bf16x8, pw);
;             int T1 = w + t1; T1 = T1 > 15 ? 15 : T1;
;             const int row0 = 16 * (w + t0) * 256, row1 = 16 * T1 * 256;
; #pragma unroll
;             for (int dt = 0; dt < 8; ++dt) {
;                 const int choff = ((2 * dt + (p4 >> 1)) ^ (2 * q4)) * 16;
;                 const s16x4 lo = __builtin_amdgcn_ds_read_tr16_b64_v4i16((LAS s16x4*)(vt + tr_base + row0 + choff));
;                 const s16x4 hi = __builtin_amdgcn_ds_read_tr16_b64_v4i16((LAS s16x4*)(vt + tr_base + row1 + choff));
;                 const bf16x8 vf = __builtin_shufflevector(lo, hi, 0, 1, 2, 3, 4, 5, 6, 7);
;                 o[dt] = __builtin_amdgcn_mfma_f32_16x16x32_bf16(vf, pf, o[dt], 0, 0, 0); }
;         }
;         const float inv = 1.0f / lsum;
;         bf16_t* op = OG + (size_t)grp * GS + qtok * 2048 + h * 128 + 4 * g4;
; #pragma unroll
;         for (int dt = 0; dt < 8; ++dt) { u32x2 wv; wv.x = pg8::cvt_pk_bf16(o[dt][0] * inv, o[dt][1] * inv); wv.y = pg8::cvt_pk_bf16(o[dt][2] * inv, o[dt][3] * inv); *(u32x2*)(op + 16 * dt) = wv; }
	v_mfma_f32_16x16x32_bf16 v[140:143], v[148:151], v[144:147], v[140:143]
	ds_read_b64_tr_b16 v[148:149], v53
	v_add_u32_e32 v53, v111, v107
	ds_read_b64_tr_b16 v[150:151], v53
	v_cvt_pk_bf16_f32 v58, v57, v58
	v_add_u32_e32 v53, v112, v99
	v_add_u32_e32 v57, v113, v99
	v_cvt_pk_bf16_f32 v59, v59, v60
	v_cvt_pk_bf16_f32 v60, v61, v62
	v_cvt_pk_bf16_f32 v61, v63, v64
	ds_read_b64_tr_b16 v[62:63], v53
	ds_read_b64_tr_b16 v[64:65], v57
	s_waitcnt lgkmcnt(0)
	v_mfma_f32_16x16x32_bf16 v[62:65], v[62:65], v[58:61], v[70:73]
	s_nop 2
	v_add_u32_e32 v70, v112, v102
	v_add_u32_e32 v72, v113, v102
	ds_read_b64_tr_b16 v[70:71], v70
	ds_read_b64_tr_b16 v[72:73], v72
	s_waitcnt lgkmcnt(0)
	v_mfma_f32_16x16x32_bf16 v[70:73], v[70:73], v[58:61], v[74:77]
	s_nop 2
	v_add_u32_e32 v74, v112, v103
	v_add_u32_e32 v76, v113, v103
	ds_read_b64_tr_b16 v[74:75], v74
	ds_read_b64_tr_b16 v[76:77], v76
	v_mfma_f32_16x16x32_bf16 v[66:69], v[148:151], v[144:147], v[66:69]
	v_mov_b32_e32 v155, v8
	v_mul_f32_e32 v93, v87, v86
	v_fma_f32 v127, -v84, v93, v87
	s_waitcnt lgkmcnt(0)
	v_mfma_f32_16x16x32_bf16 v[144:147], v[74:77], v[58:61], v[78:81]
	v_add_u32_e32 v74, v112, v104
	v_add_u32_e32 v76, v113, v104
	ds_read_b64_tr_b16 v[74:75], v74
	ds_read_b64_tr_b16 v[76:77], v76
	s_waitcnt lgkmcnt(0)
	v_mfma_f32_16x16x32_bf16 v[128:131], v[74:77], v[58:61], v[128:131]
	ds_read_b64_tr_b16 v[74:75], v53 offset:128
	ds_read_b64_tr_b16 v[76:77], v57 offset:128
	v_add_u32_e32 v53, v112, v105
	v_add_u32_e32 v57, v115, v99
	s_waitcnt lgkmcnt(0)
	v_mfma_f32_16x16x32_bf16 v[132:135], v[74:77], v[58:61], v[132:135]
	ds_read_b64_tr_b16 v[74:75], v53
	v_add_u32_e32 v53, v113, v105
	ds_read_b64_tr_b16 v[76:77], v53
	v_add_u32_e32 v53, v112, v106
	s_waitcnt lgkmcnt(0)
	v_mfma_f32_16x16x32_bf16 v[136:139], v[74:77], v[58:61], v[136:139]
	ds_read_b64_tr_b16 v[74:75], v53
	v_add_u32_e32 v53, v113, v106
	ds_read_b64_tr_b16 v[76:77], v53
	v_add_u32_e32 v53, v112, v107
	s_waitcnt lgkmcnt(0)
	v_mfma_f32_16x16x32_bf16 v[140:143], v[74:77], v[58:61], v[140:143]
	ds_read_b64_tr_b16 v[74:75], v53
	v_add_u32_e32 v53, v113, v107
	ds_read_b64_tr_b16 v[76:77], v53
	v_cvt_pk_bf16_f32 v152, v54, v55
	v_cvt_pk_bf16_f32 v153, v56, v52
	v_add_u32_e32 v56, v114, v99
	ds_read_b64_tr_b16 v[52:53], v56
	ds_read_b64_tr_b16 v[54:55], v57 offset:36864
	s_waitcnt lgkmcnt(0)
	v_mfma_f32_16x16x32_bf16 v[80:83], v[52:55], v[152:155], v[62:65]
	v_add_u32_e32 v52, v114, v102
	v_add_u32_e32 v54, v115, v102
	ds_read_b64_tr_b16 v[52:53], v52
	ds_read_b64_tr_b16 v[54:55], v54 offset:36864
	v_mfma_f32_16x16x32_bf16 v[148:151], v[74:77], v[58:61], v[66:69]
	v_fmac_f32_e32 v93, v127, v86
	v_fma_f32 v84, -v84, v93, v87
	v_div_fmas_f32 v84, v84, v86, v93
	s_waitcnt lgkmcnt(0)
	v_mfma_f32_16x16x32_bf16 v[76:79], v[52:55], v[152:155], v[70:73]
	v_add_u32_e32 v52, v114, v103
	v_add_u32_e32 v54, v115, v103
	ds_read_b64_tr_b16 v[52:53], v52
	ds_read_b64_tr_b16 v[54:55], v54 offset:36864
	s_waitcnt lgkmcnt(0)
	v_mfma_f32_16x16x32_bf16 v[72:75], v[52:55], v[152:155], v[144:147]
	v_add_u32_e32 v52, v114, v104
	v_add_u32_e32 v54, v115, v104
	ds_read_b64_tr_b16 v[52:53], v52
	ds_read_b64_tr_b16 v[54:55], v54 offset:36864
	s_waitcnt lgkmcnt(0)
	v_mfma_f32_16x16x32_bf16 v[68:71], v[52:55], v[152:155], v[128:131]
	ds_read_b64_tr_b16 v[52:53], v56 offset:128
	ds_read_b64_tr_b16 v[54:55], v57 offset:36992
	v_lshlrev_b64 v[86:87], 12, v[10:11]
	v_div_fixup_f32 v84, v84, v9, 1.0
	s_waitcnt lgkmcnt(0)
	v_mfma_f32_16x16x32_bf16 v[64:67], v[52:55], v[152:155], v[132:135]
	v_add_u32_e32 v52, v114, v105
	v_add_u32_e32 v54, v115, v105
	ds_read_b64_tr_b16 v[52:53], v52
	ds_read_b64_tr_b16 v[54:55], v54 offset:36864
	s_waitcnt lgkmcnt(0)
	v_mfma_f32_16x16x32_bf16 v[60:63], v[52:55], v[152:155], v[136:139]
	v_add_u32_e32 v52, v114, v106
	v_add_u32_e32 v54, v115, v106
	ds_read_b64_tr_b16 v[52:53], v52
	ds_read_b64_tr_b16 v[54:55], v54 offset:36864
	s_waitcnt lgkmcnt(0)
	v_mfma_f32_16x16x32_bf16 v[56:59], v[52:55], v[152:155], v[140:143]
	v_add_u32_e32 v52, v114, v107
	v_add_u32_e32 v54, v115, v107
	ds_read_b64_tr_b16 v[52:53], v52
	ds_read_b64_tr_b16 v[54:55], v54 offset:36864
	v_lshl_add_u64 v[86:87], s[14:15], 0, v[86:87]
	v_lshl_add_u64 v[86:87], v[86:87], 0, s[0:1]
	v_mov_b32_e32 v93, v8
	v_mul_f32_e32 v80, v84, v80
	v_mul_f32_e32 v81, v84, v81
	v_lshl_add_u64 v[86:87], v[86:87], 0, v[92:93]
	v_cvt_pk_bf16_f32 v80, v80, v81
	v_mul_f32_e32 v81, v84, v82
	v_mul_f32_e32 v76, v84, v76
	v_mul_f32_e32 v77, v84, v77
	v_mul_f32_e32 v82, v84, v83
	v_cvt_pk_bf16_f32 v81, v81, v82
	global_store_dwordx2 v[86:87], v[80:81], off
	v_cvt_pk_bf16_f32 v76, v76, v77
	v_mul_f32_e32 v77, v84, v78
	v_mul_f32_e32 v72, v84, v72
	v_mul_f32_e32 v73, v84, v73
	s_waitcnt lgkmcnt(0)
	v_mfma_f32_16x16x32_bf16 v[52:55], v[52:55], v[152:155], v[148:151]
	v_mul_f32_e32 v78, v84, v79
	v_cvt_pk_bf16_f32 v77, v77, v78
	global_store_dwordx2 v[86:87], v[76:77], off offset:32
	v_cvt_pk_bf16_f32 v72, v72, v73
	v_mul_f32_e32 v73, v84, v74
	v_mul_f32_e32 v68, v84, v68
	v_mul_f32_e32 v69, v84, v69
	v_mul_f32_e32 v74, v84, v75
	v_cvt_pk_bf16_f32 v73, v73, v74
	global_store_dwordx2 v[86:87], v[72:73], off offset:64
	v_cvt_pk_bf16_f32 v68, v68, v69
	v_mul_f32_e32 v69, v84, v70
	v_mul_f32_e32 v64, v84, v64
	v_mul_f32_e32 v65, v84, v65
	v_mul_f32_e32 v70, v84, v71
	v_cvt_pk_bf16_f32 v69, v69, v70
	global_store_dwordx2 v[86:87], v[68:69], off offset:96
	v_cvt_pk_bf16_f32 v64, v64, v65
	v_mul_f32_e32 v65, v84, v66
	v_mul_f32_e32 v60, v84, v60
	v_mul_f32_e32 v61, v84, v61
	v_mul_f32_e32 v66, v84, v67
	v_cvt_pk_bf16_f32 v65, v65, v66
	global_store_dwordx2 v[86:87], v[64:65], off offset:128
	v_cvt_pk_bf16_f32 v60, v60, v61
	v_mul_f32_e32 v61, v84, v62
	v_mul_f32_e32 v56, v84, v56
	v_mul_f32_e32 v57, v84, v57
	v_mul_f32_e32 v62, v84, v63
	v_cvt_pk_bf16_f32 v61, v61, v62
	global_store_dwordx2 v[86:87], v[60:61], off offset:160
	v_cvt_pk_bf16_f32 v56, v56, v57
	v_mul_f32_e32 v57, v84, v58
	v_mul_f32_e32 v52, v84, v52
	v_mul_f32_e32 v53, v84, v53
	v_mul_f32_e32 v58, v84, v59
	v_cvt_pk_bf16_f32 v57, v57, v58
	global_store_dwordx2 v[86:87], v[56:57], off offset:192
	v_cvt_pk_bf16_f32 v52, v52, v53
	v_mul_f32_e32 v53, v84, v54
	v_mul_f32_e32 v54, v84, v55
	v_cvt_pk_bf16_f32 v53, v53, v54
	global_store_dwordx2 v[86:87], v[52:53], off offset:224
	s_and_saveexec_b64 s[14:15], s[40:41]
	s_cbranch_execz .LBB0_403
; __device__ __forceinline__ unsigned cvt_pk_bf16(float lo, float hi) { unsigned r; asm volatile("v_cvt_pk_bf16_f32 %0, %1, %2" : "=v"(r) : "v"(lo), "v"(hi)); return r; }
; DI void attn0_phase(const unsigned char* QKV, bf16_t* OG, float* LSE, LAS unsigned char* lds, int tid, int bid, int G) {
;     ...
;         const float inv = 1.0f / lsum;
;         bf16_t* op = OG + (size_t)grp * GS + qtok * 2048 + h * 128 + 4 * g4;
; #pragma unroll
;         for (int dt = 0; dt < 8; ++dt) { u32x2 wv; wv.x = pg8::cvt_pk_bf16(o[dt][0] * inv, o[dt][1] * inv); wv.y = pg8::cvt_pk_bf16(o[dt][2] * inv, o[dt][3] * inv); *(u32x2*)(op + 16 * dt) = wv; }
;         if (g4 == 0) LSE[(size_t)grp * (MTOK * 16) + qtok * 16 + h] = mx * SM_SCALE + __logf(lsum);
	s_mov_b32 s0, 0x800000
	v_cmp_gt_f32_e32 vcc, s0, v9
	s_mov_b32 s0, 0x3f317217
	s_lshl_b64 s[38:39], s[38:39], 20
	v_cndmask_b32_e64 v52, 0, 32, vcc
	v_ldexp_f32 v9, v9, v52
	v_log_f32_e32 v9, v9
	v_cndmask_b32_e32 v52, 0, v126, vcc
	v_lshlrev_b64 v[10:11], 6, v[10:11]
	v_mul_f32_e32 v53, 0x3f317217, v9
	v_fma_f32 v53, v9, s0, -v53
	s_mov_b32 s0, 0x7f800000
	v_fmac_f32_e32 v53, 0x3377d1cf, v9
	v_cmp_lt_f32_e64 vcc, |v9|, s0
	v_readlane_b32 s0, v254, 23
	v_fmac_f32_e32 v53, 0x3f317217, v9
	s_add_u32 s38, s0, s38
	v_readlane_b32 s0, v254, 24
	v_cndmask_b32_e32 v9, v9, v53, vcc
	s_addc_u32 s39, s0, s39
	v_sub_f32_e32 v9, v9, v52
	v_lshl_add_u64 v[10:11], s[38:39], 0, v[10:11]
	s_lshl_b32 s0, s89, 2
	v_fmac_f32_e32 v9, 0x3db504f3, v85
	v_lshl_add_u64 v[10:11], v[10:11], 0, s[0:1]
	global_store_dword v[10:11], v9, off
	s_branch .LBB0_403

; DI void dsa_attn_phase(const bf16_t* Q1, const bf16_t* K1, const bf16_t* V1, const unsigned short* IDX, unsigned char* AO, LAS unsigned char* lds, int tid, int bid, int G) {
;     ...
;             const float mnew = fmaxf(mrun, cm); const float alpha = __builtin_amdgcn_exp2f((mrun - mnew) * SM_C); const float msc = mnew * SM_C; mrun = mnew;
;             lsum *= alpha;
; #pragma unroll
;             for (int dt = 0; dt < 8; ++dt) o[dt] = o[dt] * alpha;
;             unsigned pk[4][2];
; #pragma unroll
;             for (int tt = 0; tt < 4; ++tt) { float pp[4];
; #pragma unroll
;                 for (int j = 0; j < 4; ++j) { pp[j] = __builtin_amdgcn_exp2f(sa[tt][j] * SM_C - msc); lsum += pp[j]; }
;                 pk[tt][0] = pg8::cvt_pk_bf16(pp[0], pp[1]); pk[tt][1] = pg8::cvt_pk_bf16(pp[2], pp[3]); }
;             if (c == 3 && has_next) {
; #pragma unroll
;                 for (int ks = 0; ks < 4; ++ks) qf[ks] = (n < 4) ? __builtin_bit_cast(bf16x8, __builtin_amdgcn_raw_buffer_load_b128(qr, qlo + 64 * ks, t2 * 8192 + kvh2 * 1024, 0)) : (bf16x8){0, 0, 0, 0, 0, 0, 0, 0};
;             }
; #pragma unroll
;             for (int hf = 0; hf < 2; ++hf) {
; #pragma unroll
;                 for (int i = 0; i < 8; ++i) *(LAS u32x4*)(vwb + i * 1024) = vst[i];
;                 if (hf == 0) {
; #pragma unroll
;                     for (int i = 0; i < 8; ++i) vst[i] = __builtin_amdgcn_raw_buffer_load_b128(vr, (int)ilc[c * 64 + 32 + 4 * i + g4] * 256 + vvo, 0, 0);
;                 } else if (c < 3) {
; #pragma unroll
;                     for (int i = 0; i < 8; ++i) vst[i] = __builtin_amdgcn_raw_buffer_load_b128(vr, (int)ilc[(c + 1) * 64 + 4 * i + g4] * 256 + vvo, 0, 0);
;                 } else if (has_next) {
;                     const __amdgpu_buffer_rsrc_t vr2 = kv_rsrc(V1 + slice2);
; #pragma unroll
;                     for (int i = 0; i < 8; ++i) vst[i] = __builtin_amdgcn_raw_buffer_load_b128(vr2, (int)iln[4 * i + g4] * 256 + vvo, 0, 0);
;                 }
;                 u32x4 pw; pw.x = pk[2 * hf][0]; pw.y = pk[2 * hf][1]; pw.z = pk[2 * hf + 1][0]; pw.w = pk[2 * hf + 1][1];
;                 const bf16x8 pf = __builtin_bit_cast(bf16x8, pw);
; #pragma unroll
;                 for (int dt = 0; dt < 8; ++dt) {
;                     const s16x4 lo = __builtin_amdgcn_ds_read_tr16_b64_v4i16((LAS s16x4*)(trb[dt & 3] + 128 * (dt >> 2)));
.LBB0_3348:
	s_waitcnt vmcnt(16)
	ds_write_b128 v228, v[92:95]
	ds_write_b128 v228, v[96:99] offset:1024
	ds_write_b128 v228, v[100:103] offset:2048
	ds_write_b128 v228, v[104:107] offset:3072
	ds_write_b128 v228, v[108:111] offset:4096
	ds_write_b128 v228, v[112:115] offset:5120
	ds_write_b128 v228, v[20:23] offset:6144
	ds_write_b128 v228, v[24:27] offset:7168
	ds_read_u16 v9, v240 offset:64
	ds_read_u16 v10, v240 offset:72
	ds_read_u16 v11, v240 offset:80
	ds_read_u16 v20, v240 offset:88
	ds_read_u16 v21, v240 offset:96
	ds_read_u16 v22, v240 offset:104
	ds_read_u16 v23, v240 offset:112
	ds_read_u16 v24, v240 offset:120
	s_waitcnt lgkmcnt(7)
	v_lshl_or_b32 v9, v9, 8, v206
	s_waitcnt lgkmcnt(6)
	v_lshl_or_b32 v10, v10, 8, v206
	buffer_load_dwordx4 v[168:171], v9, s[24:27], 0 offen
	buffer_load_dwordx4 v[172:175], v10, s[24:27], 0 offen
	s_waitcnt lgkmcnt(5)
	v_lshl_or_b32 v9, v11, 8, v206
	s_waitcnt lgkmcnt(4)
	v_lshl_or_b32 v10, v20, 8, v206
	buffer_load_dwordx4 v[176:179], v9, s[24:27], 0 offen
	buffer_load_dwordx4 v[180:183], v10, s[24:27], 0 offen
	s_waitcnt lgkmcnt(3)
	v_lshl_or_b32 v9, v21, 8, v206
	s_waitcnt lgkmcnt(2)
	v_lshl_or_b32 v10, v22, 8, v206
	buffer_load_dwordx4 v[184:187], v9, s[24:27], 0 offen
	buffer_load_dwordx4 v[188:191], v10, s[24:27], 0 offen
	s_waitcnt lgkmcnt(1)
	v_lshl_or_b32 v9, v23, 8, v206
	buffer_load_dwordx4 v[20:23], v9, s[24:27], 0 offen
	s_waitcnt lgkmcnt(0)
	v_lshl_or_b32 v9, v24, 8, v206
	buffer_load_dwordx4 v[24:27], v9, s[24:27], 0 offen
	v_sub_f32_e32 v10, v239, v192
	v_mul_f32_e32 v10, 0x3e0293ee, v10
	v_exp_f32_e32 v10, v10
	v_add_u32_e32 v9, v210, v212
	ds_read_b64_tr_b16 v[92:93], v9
	ds_read_b64_tr_b16 v[94:95], v9 offset:4096
	ds_read_b64_tr_b16 v[96:97], v230
	ds_read_b64_tr_b16 v[98:99], v230 offset:4096
	v_mul_f32_e32 v102, v146, v10
	v_mul_f32_e32 v103, v147, v10
	v_mul_f32_e32 v100, v144, v10
	v_mul_f32_e32 v101, v145, v10
	v_mul_f32_e32 v106, v142, v10
	v_mul_f32_e32 v107, v143, v10
	v_mul_f32_e32 v104, v140, v10
	v_mul_f32_e32 v105, v141, v10
	v_mul_f32_e32 v112, v132, v10
	v_mul_f32_e32 v113, v133, v10
	v_mul_f32_e32 v140, v130, v10
	v_mul_f32_e32 v141, v131, v10
	ds_read_b64_tr_b16 v[142:143], v231
	ds_read_b64_tr_b16 v[144:145], v231 offset:4096
	s_waitcnt lgkmcnt(4)
	v_mfma_f32_16x16x32_bf16 v[130:133], v[92:95], v[152:155], v[100:103]
	ds_read_b64_tr_b16 v[92:93], v232
	ds_read_b64_tr_b16 v[94:95], v232 offset:4096
	v_mul_f32_e32 v108, v136, v10
	v_mul_f32_e32 v109, v137, v10
	v_mul_f32_e32 v114, v134, v10
	v_mul_f32_e32 v115, v135, v10
	s_waitcnt lgkmcnt(4)
	v_mfma_f32_16x16x32_bf16 v[134:137], v[96:99], v[152:155], v[104:107]
	ds_read_b64_tr_b16 v[96:97], v9 offset:128
	ds_read_b64_tr_b16 v[98:99], v9 offset:4224
	ds_read_b64_tr_b16 v[102:103], v230 offset:128
	ds_read_b64_tr_b16 v[104:105], v230 offset:4224
	v_mul_f32_e32 v110, v138, v10
	v_mul_f32_e32 v111, v139, v10
	v_mul_f32_e32 v138, v128, v10
	v_mul_f32_e32 v139, v129, v10
	v_mul_f32_e32 v100, v126, v10
	v_mul_f32_e32 v101, v127, v10
	s_waitcnt lgkmcnt(4)
	v_mfma_f32_16x16x32_bf16 v[126:129], v[92:95], v[152:155], v[112:115]
	ds_read_b64_tr_b16 v[92:93], v231 offset:128
	ds_read_b64_tr_b16 v[94:95], v231 offset:4224
	s_andn2_b64 vcc, exec, s[42:43]
	v_mfma_f32_16x16x32_bf16 v[156:159], v[142:145], v[152:155], v[108:111]
	ds_read_b64_tr_b16 v[106:107], v232 offset:128
	s_nop 1
	ds_read_b64_tr_b16 v[108:109], v232 offset:4224
	s_waitcnt vmcnt(7)
	ds_write_b128 v228, v[168:171]
	s_waitcnt vmcnt(6)
	ds_write_b128 v228, v[172:175] offset:1024
	s_waitcnt vmcnt(5)
	ds_write_b128 v228, v[176:179] offset:2048
	s_waitcnt vmcnt(4)
	ds_write_b128 v228, v[180:183] offset:3072
	s_waitcnt vmcnt(3)
	ds_write_b128 v228, v[184:187] offset:4096
	s_waitcnt vmcnt(2)
	ds_write_b128 v228, v[188:191] offset:5120
	s_waitcnt vmcnt(1)
	ds_write_b128 v228, v[20:23] offset:6144
	s_waitcnt lgkmcnt(13)
	v_mfma_f32_16x16x32_bf16 v[160:163], v[96:99], v[152:155], v[138:141]
	v_mul_f32_e64 v98, v124, v10
	v_mul_f32_e64 v99, v125, v10
	v_mul_f32_e32 v96, v120, v10
	v_mul_f32_e32 v97, v121, v10
	s_waitcnt vmcnt(0)
	ds_write_b128 v228, v[24:27] offset:7168
	s_waitcnt lgkmcnt(12)
	v_mfma_f32_16x16x32_bf16 v[164:167], v[102:105], v[152:155], v[98:101]
	s_nop 2
	v_mul_f32_e64 v98, v122, v10
	v_mul_f32_e64 v99, v123, v10
	s_waitcnt lgkmcnt(10)
	s_nop 0
	v_mfma_f32_16x16x32_bf16 v[120:123], v[92:95], v[152:155], v[96:99]
	v_mul_f32_e64 v94, v118, v10
	v_mul_f32_e64 v95, v119, v10
	v_mul_f32_e32 v92, v116, v10
	v_mul_f32_e32 v93, v117, v10
	s_waitcnt lgkmcnt(8)
	s_nop 0
	v_mfma_f32_16x16x32_bf16 v[116:119], v[106:109], v[152:155], v[92:95]
	s_cbranch_vccnz .LBB0_3351
	ds_read_u16 v11, v240 offset:128
	s_nop 0
	ds_read_u16 v92, v240 offset:136
	ds_read_u16 v100, v240 offset:144
	ds_read_u16 v101, v240 offset:152
	ds_read_u16 v108, v240 offset:160
	ds_read_u16 v109, v240 offset:168
	s_waitcnt lgkmcnt(5)
	v_lshl_or_b32 v11, v11, 8, v206
	s_waitcnt lgkmcnt(4)
	v_lshl_or_b32 v96, v92, 8, v206
	buffer_load_dwordx4 v[92:95], v11, s[24:27], 0 offen
	s_nop 0
	buffer_load_dwordx4 v[96:99], v96, s[24:27], 0 offen
	s_waitcnt lgkmcnt(3)
	v_lshl_or_b32 v11, v100, 8, v206
	s_waitcnt lgkmcnt(2)
	v_lshl_or_b32 v104, v101, 8, v206
	buffer_load_dwordx4 v[100:103], v11, s[24:27], 0 offen
	s_nop 0
	buffer_load_dwordx4 v[104:107], v104, s[24:27], 0 offen
	s_waitcnt lgkmcnt(1)
	v_lshl_or_b32 v11, v108, 8, v206
	s_waitcnt lgkmcnt(0)
	v_lshl_or_b32 v112, v109, 8, v206
	buffer_load_dwordx4 v[108:111], v11, s[24:27], 0 offen
	s_nop 0
	buffer_load_dwordx4 v[112:115], v112, s[24:27], 0 offen
	s_add_i32 s38, s63, 0x80
	v_add_u32_e32 v11, 0xb0, v240
	s_mov_b64 s[30:31], -1
	s_cbranch_execz .LBB0_3352
	s_mov_b64 s[12:13], s[24:25]
	s_and_b64 vcc, exec, s[30:31]
	s_cbranch_vccnz .LBB0_3355
	s_branch .LBB0_3356
